# LN2 (phase 15): ln weight/bias slices loaded once per wave; sample-row loads issued before the first wait
# speedup vs baseline: 1.1303x; 1.0027x over previous
.LBB0_2685:
	s_cmp_lt_i32 s68, 16
	s_cselect_b64 s[0:1], -1, 0
	s_cmp_gt_i32 s69, 15
	s_cselect_b64 s[2:3], -1, 0
	s_and_b64 s[0:1], s[0:1], s[2:3]
	s_andn2_b64 vcc, exec, s[0:1]
	s_cbranch_vccnz .LBB0_2693
	s_waitcnt vmcnt(0)
	v_lshl_add_u32 v28, s28, 3, v156
	s_movk_i32 s0, 0x2080
	v_cmp_gt_i32_e32 vcc, s0, v28
	s_and_saveexec_b64 s[0:1], vcc
	s_cbranch_execz .LBB0_2693
	v_lshlrev_b32_e32 v0, 2, v34
	v_and_b32_e32 v0, 0xfc, v0
	v_mov_b32_e32 v31, 0
	v_or_b32_e32 v8, 0x400, v0
	v_lshlrev_b32_e32 v30, 2, v0
	v_or_b32_e32 v10, 0x500, v0
	v_lshl_add_u64 v[32:33], s[78:79], 0, v[30:31]
	v_lshl_add_u64 v[34:35], s[80:81], 0, v[30:31]
	v_lshlrev_b32_e32 v30, 2, v8
	v_or_b32_e32 v12, 0x600, v0
	v_lshl_add_u64 v[36:37], s[78:79], 0, v[30:31]
	v_lshl_add_u64 v[38:39], s[80:81], 0, v[30:31]
	v_lshlrev_b32_e32 v30, 2, v10
	s_lshl_b32 s7, s88, 3
	v_or_b32_e32 v14, 0x700, v0
	v_lshl_add_u64 v[40:41], s[78:79], 0, v[30:31]
	v_lshl_add_u64 v[42:43], s[80:81], 0, v[30:31]
	v_lshlrev_b32_e32 v30, 2, v12
	v_or_b32_e32 v2, 0x100, v0
	v_or_b32_e32 v4, 0x200, v0
	v_or_b32_e32 v6, 0x300, v0
	v_lshl_add_u64 v[44:45], s[78:79], 0, v[30:31]
	v_lshl_add_u64 v[46:47], s[80:81], 0, v[30:31]
	v_lshlrev_b32_e32 v30, 2, v14
	s_add_u32 s0, s34, 0x1eea2200
	v_lshl_add_u64 v[48:49], s[78:79], 0, v[30:31]
	v_lshl_add_u64 v[50:51], s[80:81], 0, v[30:31]
	s_addc_u32 s1, s35, 0
	s_mov_b64 s[2:3], 0
	s_movk_i32 s10, 0x1fff
	s_mov_b32 s11, 0xc000
	s_mov_b64 s[4:5], 0x824a000
	s_mov_b32 s6, 0x3f9837f0
	v_lshlrev_b32_e32 v52, 2, v2
	v_lshlrev_b32_e32 v54, 2, v4
	v_lshlrev_b32_e32 v56, 2, v6
	v_mov_b32_e32 v78, 0x3727c5ac
	s_mov_b32 s12, 0x800000
	v_lshlrev_b32_e32 v58, 2, v8
	v_lshlrev_b32_e32 v60, 2, v10
	v_lshlrev_b32_e32 v62, 2, v12
	v_lshlrev_b32_e32 v64, 2, v14
	s_movk_i32 s13, 0x207f
	v_lshlrev_b32_e32 v30, 2, v0
	global_load_dwordx4 v[174:177], v[32:33], off
	global_load_dwordx4 v[182:185], v[32:33], off offset:1024
	global_load_dwordx4 v[190:193], v[32:33], off offset:2048
	global_load_dwordx4 v[198:201], v[32:33], off offset:3072
	global_load_dwordx4 v[178:181], v[34:35], off
	global_load_dwordx4 v[186:189], v[34:35], off offset:1024
	global_load_dwordx4 v[194:197], v[34:35], off offset:2048
	global_load_dwordx4 v[202:205], v[34:35], off offset:3072
	global_load_dwordx4 v[206:209], v[36:37], off
	global_load_dwordx4 v[210:213], v[38:39], off
	global_load_dwordx4 v[214:217], v[40:41], off
	global_load_dwordx4 v[218:221], v[42:43], off
	global_load_dwordx4 v[222:225], v[44:45], off
	global_load_dwordx4 v[226:229], v[46:47], off
	global_load_dwordx4 v[230:233], v[48:49], off
	global_load_dwordx4 v[234:237], v[50:51], off
	s_branch .LBB0_2689
.LBB0_2688:
	s_or_b64 exec, exec, s[8:9]
	v_pk_add_f32 v[10:11], v[72:73], v[24:25]
	v_pk_add_f32 v[80:81], v[70:71], v[26:27]
	v_add_f32_e32 v13, v16, v17
	v_pk_add_f32 v[10:11], v[10:11], v[80:81]
	v_add_f32_e32 v69, v18, v19
	v_add_f32_e32 v11, 0, v11
	v_add_f32_e32 v23, v10, v11
	v_pk_add_f32 v[10:11], v[76:77], v[20:21]
	v_pk_add_f32 v[80:81], v[12:13], v[68:69]
	v_pk_add_f32 v[10:11], v[10:11], v[10:11] op_sel_hi:[0,1]
	v_mov_b32_e32 v15, v11
	v_pk_add_f32 v[10:11], v[14:15], v[22:23]
	v_add_f32_e32 v83, v0, v1
	v_pk_add_f32 v[10:11], v[80:81], v[10:11]
	v_pk_add_f32 v[80:81], v[74:75], v[8:9]
	v_pk_add_f32 v[10:11], v[10:11], v[10:11] op_sel_hi:[0,1]
	v_pk_add_f32 v[80:81], v[80:81], v[80:81] op_sel_hi:[0,1]
	v_add_f32_e32 v85, v2, v3
	v_mov_b32_e32 v82, v4
	v_mov_b32_e32 v84, v5
	v_mov_b32_e32 v80, v6
	v_mov_b32_e32 v10, v7
	v_pk_add_f32 v[82:83], v[82:83], v[84:85]
	v_pk_add_f32 v[10:11], v[80:81], v[10:11]
	v_mov_b32_e32 v59, v31
	v_pk_add_f32 v[10:11], v[82:83], v[10:11]
	v_mov_b32_e32 v61, v31
	v_add_f32_e32 v10, v10, v11
	v_mov_b32_e32 v63, v31
	v_add_u32_e32 v28, s7, v28
	v_add_f32_dpp v10, v10, v10 quad_perm:[1,0,3,2] row_mask:0xf bank_mask:0xf bound_ctrl:1
	v_mov_b32_e32 v65, v31
	s_nop 0
	v_add_f32_dpp v10, v10, v10 quad_perm:[2,3,0,1] row_mask:0xf bank_mask:0xf bound_ctrl:1
	s_nop 1
	v_add_f32_dpp v10, v10, v10 row_half_mirror row_mask:0xf bank_mask:0xf bound_ctrl:1
	s_nop 1
	v_add_f32_dpp v10, v10, v10 row_mirror row_mask:0xf bank_mask:0xf bound_ctrl:1
	s_nop 0
	v_readlane_b32 s14, v10, 16
	v_readlane_b32 s15, v10, 48
	v_readlane_b32 s8, v10, 0
	v_readlane_b32 s9, v10, 32
	v_mov_b32_e32 v10, s14
	v_mov_b32_e32 v11, s15
	v_pk_add_f32 v[10:11], s[8:9], v[10:11]
	s_nop 0
	v_add_f32_e32 v11, v10, v11
	v_fmac_f32_e32 v25, 0xba000000, v11
	v_fmac_f32_e32 v24, 0xba000000, v11
	v_fmac_f32_e32 v27, 0xba000000, v11
	v_fmac_f32_e32 v73, 0xba000000, v11
	v_fmac_f32_e32 v26, 0xba000000, v11
	v_fmac_f32_e32 v72, 0xba000000, v11
	v_mov_b32_e32 v82, v25
	v_mov_b32_e32 v83, v24
	v_fmac_f32_e32 v71, 0xba000000, v11
	v_fmac_f32_e32 v70, 0xba000000, v11
	v_mov_b32_e32 v80, v73
	v_mov_b32_e32 v81, v72
	v_pk_mul_f32 v[82:83], v[82:83], v[82:83]
	v_mov_b32_e32 v84, v27
	v_mov_b32_e32 v85, v26
	v_pk_fma_f32 v[80:81], v[80:81], v[80:81], v[82:83]
	v_mov_b32_e32 v82, v71
	v_mov_b32_e32 v83, v70
	v_pk_mul_f32 v[84:85], v[84:85], v[84:85]
	v_fmac_f32_e32 v76, 0xba000000, v11
	v_pk_fma_f32 v[82:83], v[82:83], v[82:83], v[84:85]
	v_fmac_f32_e32 v21, 0xba000000, v11
	v_fmac_f32_e32 v77, 0xba000000, v11
	v_pk_add_f32 v[80:81], v[80:81], v[82:83]
	v_fmac_f32_e32 v20, 0xba000000, v11
	v_mov_b32_e32 v90, v77
	v_mov_b32_e32 v91, v21
	v_mov_b32_e32 v21, v76
	v_pk_add_f32 v[88:89], v[80:81], v[80:81] op_sel_hi:[0,1]
	v_pk_mul_f32 v[80:81], v[90:91], v[90:91]
	v_pk_mul_f32 v[76:77], v[20:21], v[20:21]
	v_fmac_f32_e32 v16, 0xba000000, v11
	v_pk_mov_b32 v[92:93], v[76:77], v[80:81] op_sel:[1,0]
	v_mov_b32_e32 v77, v81
	v_pk_add_f32 v[76:77], v[92:93], v[76:77]
	v_fmac_f32_e32 v17, 0xba000000, v11
	v_pk_add_f32 v[76:77], v[76:77], v[76:77] op_sel_hi:[0,1]
	v_fmac_f32_e32 v18, 0xba000000, v11
	v_mul_f32_e32 v76, v16, v16
	v_fmac_f32_e32 v19, 0xba000000, v11
	v_pk_fma_f32 v[92:93], v[16:17], v[16:17], v[76:77] op_sel_hi:[1,1,0]
	v_mul_f32_e32 v76, v18, v18
	v_pk_fma_f32 v[94:95], v[18:19], v[18:19], v[76:77] op_sel_hi:[1,1,0]
	v_fmac_f32_e32 v22, 0xba000000, v11
	v_fmac_f32_e32 v14, 0xba000000, v11
	v_fmac_f32_e32 v68, 0xba000000, v11
	v_fmac_f32_e32 v12, 0xba000000, v11
	v_mul_f32_e32 v92, v12, v12
	v_mul_f32_e32 v94, v68, v68
	v_mul_f32_e32 v76, v14, v14
	v_mul_f32_e32 v88, v22, v22
	v_fmac_f32_e32 v74, 0xba000000, v11
	v_fmac_f32_e32 v9, 0xba000000, v11
	v_fmac_f32_e32 v75, 0xba000000, v11
	v_pk_add_f32 v[92:93], v[92:93], v[94:95]
	v_pk_add_f32 v[76:77], v[76:77], v[88:89]
	v_fmac_f32_e32 v8, 0xba000000, v11
	v_mov_b32_e32 v88, v75
	v_mov_b32_e32 v89, v9
	v_mov_b32_e32 v9, v74
	v_pk_add_f32 v[76:77], v[92:93], v[76:77]
	v_pk_mul_f32 v[92:93], v[88:89], v[88:89]
	v_pk_mul_f32 v[74:75], v[8:9], v[8:9]
	v_fmamk_f32 v0, v11, 0xba000000, v0
	v_pk_mov_b32 v[94:95], v[74:75], v[92:93] op_sel:[1,0]
	v_mov_b32_e32 v75, v93
	v_pk_add_f32 v[74:75], v[94:95], v[74:75]
	v_fmamk_f32 v1, v11, 0xba000000, v1
	v_pk_add_f32 v[74:75], v[74:75], v[74:75] op_sel_hi:[0,1]
	v_fmac_f32_e32 v2, 0xba000000, v11
	v_mul_f32_e32 v74, v0, v0
	v_fmamk_f32 v3, v11, 0xba000000, v3
	v_pk_fma_f32 v[92:93], v[0:1], v[0:1], v[74:75] op_sel_hi:[1,1,0]
	v_mul_f32_e32 v74, v2, v2
	v_pk_add_f32 v[76:77], v[76:77], v[76:77] op_sel_hi:[0,1]
	v_pk_fma_f32 v[94:95], v[2:3], v[2:3], v[74:75] op_sel_hi:[1,1,0]
	v_fmamk_f32 v97, v11, 0xba000000, v7
	v_fmamk_f32 v96, v11, 0xba000000, v6
	v_fmamk_f32 v5, v11, 0xba000000, v5
	v_fmac_f32_e32 v4, 0xba000000, v11
	v_mul_f32_e32 v92, v4, v4
	v_mul_f32_e32 v94, v5, v5
	v_mul_f32_e32 v74, v96, v96
	v_mul_f32_e32 v76, v97, v97
	v_pk_add_f32 v[6:7], v[92:93], v[94:95]
	v_pk_add_f32 v[74:75], v[74:75], v[76:77]
	v_mov_b32_e32 v10, v73
	v_pk_add_f32 v[6:7], v[6:7], v[74:75]
	v_mov_b32_e32 v11, v25
	v_add_f32_e32 v6, v6, v7
	v_mov_b32_e32 v73, v24
	s_nop 0
	v_add_f32_dpp v6, v6, v6 quad_perm:[1,0,3,2] row_mask:0xf bank_mask:0xf bound_ctrl:1
	s_nop 1
	v_add_f32_dpp v6, v6, v6 quad_perm:[2,3,0,1] row_mask:0xf bank_mask:0xf bound_ctrl:1
	s_nop 1
	v_add_f32_dpp v6, v6, v6 row_half_mirror row_mask:0xf bank_mask:0xf bound_ctrl:1
	s_nop 1
	v_add_f32_dpp v6, v6, v6 row_mirror row_mask:0xf bank_mask:0xf bound_ctrl:1
	s_nop 0
	v_readlane_b32 s14, v6, 16
	v_readlane_b32 s15, v6, 48
	v_readlane_b32 s8, v6, 0
	v_readlane_b32 s9, v6, 32
	v_mov_b32_e32 v6, s14
	v_mov_b32_e32 v7, s15
	v_pk_add_f32 v[6:7], s[8:9], v[6:7]
	s_nop 0
	v_add_f32_e32 v6, v6, v7
	v_fmamk_f32 v6, v6, 0x3a000000, v78
	v_mul_f32_e32 v7, 0x4b800000, v6
	v_cmp_gt_f32_e32 vcc, s12, v6
	s_nop 1
	v_cndmask_b32_e32 v6, v6, v7, vcc
	v_rsq_f32_e32 v13, v6
	v_mov_b32_e32 v6, v71
	v_mov_b32_e32 v7, v27
	v_mov_b32_e32 v71, v26
	v_mul_f32_e32 v15, 0x45800000, v13
	v_cndmask_b32_e32 v92, v13, v15, vcc
	v_pk_mul_f32 v[10:11], v[10:11], v[92:93] op_sel_hi:[1,0]
	v_pk_mul_f32 v[6:7], v[6:7], v[92:93] op_sel_hi:[1,0]
	s_nop 1
	v_mov_b32_e32 v80, v174
	v_mov_b32_e32 v81, v175
	v_mov_b32_e32 v82, v176
	v_mov_b32_e32 v83, v177
	v_mov_b32_e32 v84, v178
	v_mov_b32_e32 v85, v179
	v_mov_b32_e32 v86, v180
	v_mov_b32_e32 v87, v181
	v_pk_fma_f32 v[74:75], v[80:81], v[10:11], v[84:85]
	v_pk_fma_f32 v[76:77], v[82:83], v[6:7], v[86:87]
	v_lshl_add_u64 v[6:7], v[66:67], 0, v[30:31]
	global_store_dwordx4 v[6:7], v[74:77], off nt
	s_nop 0
	v_pk_mul_f32 v[10:11], v[70:71], v[92:93] op_sel_hi:[1,0]
	v_pk_mul_f32 v[24:25], v[72:73], v[92:93] op_sel_hi:[1,0]
	v_pk_mul_f32 v[20:21], v[20:21], v[92:93] op_sel_hi:[1,0]
	v_pk_mul_f32 v[16:17], v[16:17], v[92:93] op_sel_hi:[1,0]
	v_mov_b32_e32 v15, v22
	v_mov_b32_e32 v13, v68
	v_pk_mul_f32 v[14:15], v[14:15], v[92:93] op_sel_hi:[1,0]
	v_pk_mul_f32 v[2:3], v[2:3], v[92:93] op_sel_hi:[1,0]
	v_pk_mul_f32 v[0:1], v[0:1], v[92:93] op_sel_hi:[1,0]
	v_cmp_lt_i32_e32 vcc, s13, v28
	v_pk_mul_f32 v[4:5], v[4:5], v[92:93] op_sel_hi:[1,0]
	s_or_b64 s[2:3], vcc, s[2:3]
	s_nop 1
	v_mov_b32_e32 v74, v182
	v_mov_b32_e32 v75, v183
	v_mov_b32_e32 v76, v184
	v_mov_b32_e32 v77, v185
	v_mov_b32_e32 v80, v186
	v_mov_b32_e32 v81, v187
	v_mov_b32_e32 v82, v188
	v_mov_b32_e32 v83, v189
	v_pk_fma_f32 v[24:25], v[74:75], v[24:25], v[80:81]
	v_pk_fma_f32 v[26:27], v[76:77], v[10:11], v[82:83]
	global_store_dwordx4 v[6:7], v[24:27], off offset:1024 nt
	s_nop 0
	v_pk_mul_f32 v[10:11], v[90:91], v[92:93] op_sel_hi:[1,0]
	s_nop 1
	v_mov_b32_e32 v24, v190
	v_mov_b32_e32 v25, v191
	v_mov_b32_e32 v26, v192
	v_mov_b32_e32 v27, v193
	v_mov_b32_e32 v70, v194
	v_mov_b32_e32 v71, v195
	v_mov_b32_e32 v72, v196
	v_mov_b32_e32 v73, v197
	v_pk_fma_f32 v[24:25], v[24:25], v[20:21], v[70:71]
	v_pk_fma_f32 v[26:27], v[26:27], v[10:11], v[72:73]
	global_store_dwordx4 v[6:7], v[24:27], off offset:2048 nt
	s_nop 0
	v_pk_mul_f32 v[10:11], v[18:19], v[92:93] op_sel_hi:[1,0]
	v_pk_mul_f32 v[20:21], v[88:89], v[92:93] op_sel_hi:[1,0]
	s_nop 1
	v_mov_b32_e32 v24, v198
	v_mov_b32_e32 v25, v199
	v_mov_b32_e32 v26, v200
	v_mov_b32_e32 v27, v201
	v_mov_b32_e32 v70, v202
	v_mov_b32_e32 v71, v203
	v_mov_b32_e32 v72, v204
	v_mov_b32_e32 v73, v205
	v_pk_fma_f32 v[16:17], v[24:25], v[16:17], v[70:71]
	v_pk_fma_f32 v[18:19], v[26:27], v[10:11], v[72:73]
	global_store_dwordx4 v[6:7], v[16:19], off offset:3072 nt
	s_nop 0
	v_pk_mul_f32 v[10:11], v[12:13], v[92:93] op_sel_hi:[1,0]
	v_lshl_add_u64 v[6:7], v[66:67], 0, v[58:59]
	s_nop 1
	v_mov_b32_e32 v16, v206
	v_mov_b32_e32 v17, v207
	v_mov_b32_e32 v18, v208
	v_mov_b32_e32 v19, v209
	v_mov_b32_e32 v24, v210
	v_mov_b32_e32 v25, v211
	v_mov_b32_e32 v26, v212
	v_mov_b32_e32 v27, v213
	v_pk_fma_f32 v[10:11], v[10:11], v[16:17], v[24:25]
	v_pk_fma_f32 v[12:13], v[14:15], v[18:19], v[26:27]
	global_store_dwordx4 v[6:7], v[10:13], off nt
	s_nop 0
	v_pk_mul_f32 v[6:7], v[8:9], v[92:93] op_sel_hi:[1,0]
	v_lshl_add_u64 v[18:19], v[66:67], 0, v[60:61]
	s_nop 1
	v_mov_b32_e32 v10, v214
	v_mov_b32_e32 v11, v215
	v_mov_b32_e32 v12, v216
	v_mov_b32_e32 v13, v217
	v_mov_b32_e32 v14, v218
	v_mov_b32_e32 v15, v219
	v_mov_b32_e32 v16, v220
	v_mov_b32_e32 v17, v221
	v_pk_fma_f32 v[6:7], v[6:7], v[10:11], v[14:15]
	v_pk_fma_f32 v[8:9], v[20:21], v[12:13], v[16:17]
	global_store_dwordx4 v[18:19], v[6:9], off nt
	s_nop 0
	v_lshl_add_u64 v[14:15], v[66:67], 0, v[62:63]
	s_nop 1
	v_mov_b32_e32 v6, v222
	v_mov_b32_e32 v7, v223
	v_mov_b32_e32 v8, v224
	v_mov_b32_e32 v9, v225
	v_mov_b32_e32 v10, v226
	v_mov_b32_e32 v11, v227
	v_mov_b32_e32 v12, v228
	v_mov_b32_e32 v13, v229
	v_pk_fma_f32 v[0:1], v[0:1], v[6:7], v[10:11]
	v_pk_fma_f32 v[2:3], v[2:3], v[8:9], v[12:13]
	global_store_dwordx4 v[14:15], v[0:3], off nt
	s_nop 0
	v_pk_mul_f32 v[12:13], v[96:97], v[92:93] op_sel_hi:[1,0]
	v_lshl_add_u64 v[10:11], v[66:67], 0, v[64:65]
	s_nop 1
	v_mov_b32_e32 v0, v230
	v_mov_b32_e32 v1, v231
	v_mov_b32_e32 v2, v232
	v_mov_b32_e32 v3, v233
	v_mov_b32_e32 v6, v234
	v_mov_b32_e32 v7, v235
	v_mov_b32_e32 v8, v236
	v_mov_b32_e32 v9, v237
	v_pk_fma_f32 v[0:1], v[4:5], v[0:1], v[6:7]
	v_pk_fma_f32 v[2:3], v[12:13], v[2:3], v[8:9]
	global_store_dwordx4 v[10:11], v[0:3], off nt
	s_andn2_b64 exec, exec, s[2:3]
	s_cbranch_execz .LBB0_2693
.LBB0_2689:
	v_ashrrev_i32_e32 v29, 31, v28
	v_lshlrev_b64 v[0:1], 13, v[28:29]
	v_lshl_add_u64 v[66:67], s[82:83], 0, v[0:1]
	v_cmp_lt_i32_e32 vcc, s10, v28
	s_and_saveexec_b64 s[8:9], vcc
	s_xor_b64 s[8:9], exec, s[8:9]
	s_cbranch_execz .LBB0_2691
	v_add_u32_e32 v2, 0xffffe004, v28
	v_mov_b64_e32 v[0:1], s[34:35]
	v_mad_u64_u32 v[0:1], s[14:15], v2, s11, v[0:1]
	v_add_u32_e32 v2, 0xffffe000, v28
	v_mov_b32_e32 v3, v31
	v_lshlrev_b64 v[2:3], 13, v[2:3]
	v_lshl_add_u64 v[76:77], s[0:1], 0, v[2:3]
	v_lshl_add_u64 v[128:129], v[0:1], 0, s[4:5]
	v_mov_b32_e32 v53, v31
	v_mov_b32_e32 v55, v31
	v_mov_b32_e32 v57, v31
	v_mov_b32_e32 v59, v31
	v_mov_b32_e32 v61, v31
	v_mov_b32_e32 v63, v31
	v_lshl_add_u64 v[8:9], v[128:129], 0, v[30:31]
	v_lshl_add_u64 v[72:73], v[76:77], 0, v[30:31]
	v_lshl_add_u64 v[74:75], v[128:129], 0, v[52:53]
	v_lshl_add_u64 v[80:81], v[128:129], 0, v[54:55]
	v_lshl_add_u64 v[82:83], v[128:129], 0, v[56:57]
	v_lshl_add_u64 v[84:85], v[128:129], 0, v[58:59]
	v_lshl_add_u64 v[86:87], v[76:77], 0, v[58:59]
	v_lshl_add_u64 v[92:93], v[128:129], 0, v[60:61]
	v_lshl_add_u64 v[94:95], v[76:77], 0, v[60:61]
	v_lshl_add_u64 v[100:101], v[128:129], 0, v[62:63]
	v_lshl_add_u64 v[102:103], v[76:77], 0, v[62:63]
	v_lshl_add_u64 v[116:117], v[66:67], 0, v[30:31]
	v_mov_b32_e32 v65, v31
	global_load_dwordx4 v[0:3], v[8:9], off
	global_load_dwordx4 v[4:7], v[72:73], off
	s_nop 0
	global_load_dwordx4 v[8:11], v[72:73], off offset:1024
	global_load_dwordx4 v[12:15], v[72:73], off offset:2048
	global_load_dwordx4 v[16:19], v[80:81], off
	global_load_dwordx4 v[20:23], v[82:83], off
	global_load_dwordx4 v[24:27], v[74:75], off
	global_load_dwordx4 v[68:71], v[72:73], off offset:3072
	s_nop 0
	global_load_dwordx4 v[72:75], v[84:85], off
	global_load_dwordx4 v[80:83], v[86:87], off
	s_nop 0
	global_load_dwordx4 v[84:87], v[92:93], off
	global_load_dwordx4 v[88:91], v[94:95], off
	s_nop 0
	global_load_dwordx4 v[92:95], v[100:101], off
	global_load_dwordx4 v[96:99], v[102:103], off
	s_nop 0
	global_load_dwordx4 v[100:103], v[116:117], off
	global_load_dwordx4 v[104:107], v[116:117], off offset:1024
	global_load_dwordx4 v[108:111], v[116:117], off offset:2048
	global_load_dwordx4 v[112:115], v[116:117], off offset:3072
	v_lshl_add_u64 v[116:117], v[66:67], 0, v[58:59]
	v_lshl_add_u64 v[120:121], v[66:67], 0, v[60:61]
	v_lshl_add_u64 v[124:125], v[66:67], 0, v[62:63]
	v_lshl_add_u64 v[128:129], v[128:129], 0, v[64:65]
	v_lshl_add_u64 v[76:77], v[76:77], 0, v[64:65]
	global_load_dwordx4 v[116:119], v[116:117], off
	global_load_dwordx4 v[120:123], v[120:121], off
	global_load_dwordx4 v[124:127], v[124:125], off
	s_nop 0
	global_load_dwordx4 v[128:131], v[128:129], off
	s_nop 0
	global_load_dwordx4 v[132:135], v[76:77], off
	v_lshl_add_u64 v[76:77], v[66:67], 0, v[64:65]
	global_load_dwordx4 v[136:139], v[76:77], off
	s_waitcnt vmcnt(5)
	v_pk_mul_f32 v[2:3], v[2:3], v[6:7]
	v_pk_mul_f32 v[0:1], v[0:1], v[4:5]
	v_pk_mul_f32 v[4:5], v[26:27], v[10:11]
	v_pk_mul_f32 v[6:7], v[24:25], v[8:9]
	v_pk_mul_f32 v[8:9], v[18:19], v[14:15]
	v_pk_mul_f32 v[10:11], v[16:17], v[12:13]
	v_pk_mul_f32 v[12:13], v[22:23], v[70:71]
	v_pk_mul_f32 v[14:15], v[20:21], v[68:69]
	v_pk_mul_f32 v[22:23], v[74:75], v[82:83]
	v_pk_mul_f32 v[24:25], v[72:73], v[80:81]
	v_pk_mul_f32 v[26:27], v[86:87], v[90:91]
	v_pk_mul_f32 v[68:69], v[84:85], v[88:89]
	v_pk_mul_f32 v[74:75], v[94:95], v[98:99]
	v_pk_mul_f32 v[76:77], v[92:93], v[96:97]
	v_pk_fma_f32 v[80:81], v[102:103], s[6:7], v[2:3] op_sel_hi:[1,0,1]
	v_pk_fma_f32 v[82:83], v[100:101], s[6:7], v[0:1] op_sel_hi:[1,0,1]
	v_pk_fma_f32 v[70:71], v[106:107], s[6:7], v[4:5] op_sel_hi:[1,0,1]
	v_pk_fma_f32 v[72:73], v[104:105], s[6:7], v[6:7] op_sel_hi:[1,0,1]
	v_pk_fma_f32 v[20:21], v[110:111], s[6:7], v[8:9] op_sel_hi:[1,0,1]
	v_pk_fma_f32 v[10:11], v[108:109], s[6:7], v[10:11] op_sel_hi:[1,0,1]
	v_pk_fma_f32 v[18:19], v[114:115], s[6:7], v[12:13] op_sel_hi:[1,0,1]
	v_pk_fma_f32 v[16:17], v[112:113], s[6:7], v[14:15] op_sel_hi:[1,0,1]
	v_pk_fma_f32 v[14:15], v[118:119], s[6:7], v[22:23] op_sel_hi:[1,0,1]
	v_pk_fma_f32 v[12:13], v[116:117], s[6:7], v[24:25] op_sel_hi:[1,0,1]
	s_waitcnt vmcnt(0)
	v_pk_fma_f32 v[8:9], v[122:123], s[6:7], v[26:27] op_sel_hi:[1,0,1]
	v_pk_fma_f32 v[22:23], v[120:121], s[6:7], v[68:69] op_sel_hi:[1,0,1]
	v_pk_fma_f32 v[2:3], v[126:127], s[6:7], v[74:75] op_sel_hi:[1,0,1]
	v_pk_mul_f32 v[4:5], v[130:131], v[134:135]
	v_pk_mul_f32 v[24:25], v[128:129], v[132:133]
	v_pk_fma_f32 v[0:1], v[124:125], s[6:7], v[76:77] op_sel_hi:[1,0,1]
	v_pk_fma_f32 v[6:7], v[138:139], s[6:7], v[4:5] op_sel_hi:[1,0,1]
	v_pk_fma_f32 v[4:5], v[136:137], s[6:7], v[24:25] op_sel_hi:[1,0,1]
	v_mov_b32_e32 v75, v8
	v_mov_b32_e32 v74, v23
	v_mov_b32_e32 v8, v22
	v_mov_b32_e32 v22, v15
	v_mov_b32_e32 v68, v13
	v_mov_b32_e32 v77, v20
	v_mov_b32_e32 v76, v11
	v_mov_b32_e32 v20, v10
	v_mov_b32_e32 v26, v71
	v_mov_b32_e32 v24, v73
	v_mov_b32_e32 v27, v81
	v_mov_b32_e32 v71, v80
	v_mov_b32_e32 v25, v83
	v_mov_b32_e32 v73, v82
